# v20 without the per-segment s_setprio raise in the attention loop
# baseline (speedup 1.0000x reference)
; #define SBAR() __builtin_amdgcn_sched_barrier(0)
; #define MFMA8Q(A, B, C) __builtin_amdgcn_mfma_scale_f32_32x32x64_f8f6f4(A, B, C, 0, 0, 0, SCL1, 0, 0x7C7C7C7C)
; __device__ __forceinline__ v8i ld32(const char* p0, const char* p1) { const u32x4 a = *(const u32x4*)p0, b = *(const u32x4*)p1; return (v8i){(int)a.x, (int)a.y, (int)a.z, (int)a.w, (int)b.x, (int)b.y, (int)b.z, (int)b.w}; }
; #define DMA(slot, t) do { \
;     __builtin_amdgcn_global_load_lds((const unsigned*)(Kg + (long)(t) * (64 * 256)), (LAS unsigned*)(L3 + K_OFF + (slot) * SHM_T + wid * 1024), 16, 0, 0); \
;     __builtin_amdgcn_global_load_lds((const unsigned*)(Vg + (long)(t) * 8192), (LAS unsigned*)(L3 + (slot) * SHM_T + wid * 1024), 16, 0, 0); } while (0)
; #define QKT(P0, P1, b) qkt(P0, P1, nm, K_lds + (b) * SHM_T, qr, ko, c00, c01, c10, c11)
; __device__ __forceinline__ void finishSM(f32x16& p0, f32x16& p1, v8i& pf) {
;   for (int r = 0; r < 16; ++r) p1[r] = __builtin_amdgcn_exp2f(p1[r]);
; #pragma unroll
;   for (int j = 0; j < 4; ++j) {
;     int a = __builtin_amdgcn_cvt_pk_fp8_f32(p0[4 * j], p0[4 * j + 1], 0, false); a = __builtin_amdgcn_cvt_pk_fp8_f32(p0[4 * j + 2], p0[4 * j + 3], a, true);
;     int b = __builtin_amdgcn_cvt_pk_fp8_f32(p1[4 * j], p1[4 * j + 1], 0, false); b = __builtin_amdgcn_cvt_pk_fp8_f32(p1[4 * j + 2], p1[4 * j + 3], b, true);
;     auto rr = __builtin_amdgcn_permlane32_swap((unsigned)a, (unsigned)b, false, false);
;     pf[2 * j] = (int)rr[0]; pf[2 * j + 1] = (int)rr[1]; }
; }
; __device__ __forceinline__ void qkt(f32x16& p0, f32x16& p1, const f32x16& nm, const char* Ks, const v8i* qr, int ko, int c00, int c01, int c10, int c11) {
;   { const v8i a0 = ld32(Ks + ko + c00, Ks + ko + c01), a1 = ld32(Ks + 4096 + ko + c00, Ks + 4096 + ko + c01);
;     p0 = MFMA8Q(a0, qr[0], nm); p1 = MFMA8Q(a1, qr[0], nm); }
;   { const v8i a0 = ld32(Ks + ko + c10, Ks + ko + c11), a1 = ld32(Ks + 4096 + ko + c10, Ks + 4096 + ko + c11);
;     p0 = MFMA8Q(a0, qr[1], p0); p1 = MFMA8Q(a1, qr[1], p1); }
; }
; __device__ __forceinline__ void body(const unsigned char* Q8b, const unsigned char* K8h, const unsigned char* VT8h, const bf16_t* Gb, bf16_t* Ob, int seq, char* lds, const int wid, ...
;     ...
;     SBAR(); QKT(pB0, pB1, (s0 + 1) & 3);
;     finishSM(pA0, pA1, pf); PIPE1(); SBAR();
;     DMA((s0 + 3) & 3, i + 3);
;     SBAR();
;     HALF2(pB0, pB1, alB, s0);
.LBB0_374:
	ds_read_b128 v[2:5], v242 offset:40960
	ds_read_b128 v[6:9], v243 offset:40960
	ds_read_b128 v[128:131], v242 offset:45056
	ds_read_b128 v[132:135], v243 offset:45056
	ds_read_b128 v[194:197], v244 offset:40960
	ds_read_b128 v[198:201], v245 offset:40960
	ds_read_b128 v[246:249], v244 offset:45056
	ds_read_b128 v[250:253], v245 offset:45056
	v_exp_f32_e32 v1, v112
	v_exp_f32_e32 v10, v113
	v_exp_f32_e32 v11, v114
	v_exp_f32_e32 v12, v115
	s_waitcnt lgkmcnt(6)
	v_mfma_scale_f32_32x32x64_f8f6f4 v[160:175], v[2:9], v[176:183], v[96:111], v240, v239 op_sel_hi:[0,0,0]
	v_exp_f32_e32 v6, v116
	v_exp_f32_e32 v7, v117
	v_exp_f32_e32 v8, v118
	v_exp_f32_e32 v9, v119
	v_cvt_pk_fp8_f32 v5, v6, v7
	v_cvt_pk_fp8_f32 v3, v1, v10
	v_cvt_pk_fp8_f32 v5, v8, v9 op_sel:[0,0,1]
	s_waitcnt lgkmcnt(4)
	v_mfma_scale_f32_32x32x64_f8f6f4 v[128:143], v[128:135], v[176:183], v[96:111], v240, v239 op_sel_hi:[0,0,0]
	v_exp_f32_e32 v13, v120
	v_exp_f32_e32 v14, v121
	v_exp_f32_e32 v15, v122
	v_exp_f32_e32 v112, v123
	v_cvt_pk_fp8_f32 v2, v144, v145
	v_cvt_pk_fp8_f32 v4, v148, v149
	v_cvt_pk_fp8_f32 v6, v152, v153
	v_cvt_pk_fp8_f32 v7, v13, v14
	v_cvt_pk_fp8_f32 v8, v156, v157
	v_cvt_pk_fp8_f32 v2, v146, v147 op_sel:[0,0,1]
	v_cvt_pk_fp8_f32 v3, v11, v12 op_sel:[0,0,1]
	v_cvt_pk_fp8_f32 v4, v150, v151 op_sel:[0,0,1]
	v_cvt_pk_fp8_f32 v6, v154, v155 op_sel:[0,0,1]
	v_cvt_pk_fp8_f32 v7, v15, v112 op_sel:[0,0,1]
	v_cvt_pk_fp8_f32 v8, v158, v159 op_sel:[0,0,1]
	s_waitcnt lgkmcnt(2)
	v_mfma_scale_f32_32x32x64_f8f6f4 v[160:175], v[194:201], v[184:191], v[160:175], v240, v239 op_sel_hi:[0,0,0]
	v_exp_f32_e32 v113, v124
	v_exp_f32_e32 v114, v125
	v_exp_f32_e32 v1, v126
	v_exp_f32_e32 v10, v127
	v_cvt_pk_fp8_f32 v9, v113, v114
	s_nop 0
	v_cvt_pk_fp8_f32 v9, v1, v10 op_sel:[0,0,1]
	s_waitcnt lgkmcnt(0)
	v_mfma_scale_f32_32x32x64_f8f6f4 v[128:143], v[246:253], v[184:191], v[128:143], v240, v239 op_sel_hi:[0,0,0]
	s_add_i32 m0, s68, 0xe000
	s_nop 0
	global_load_lds_dwordx4 v192, s[98:99]
	s_add_i32 m0, s68, 0x6000
	s_nop 0
	global_load_lds_dwordx4 v193, s[100:101]
	ds_read_b128 v[194:197], v254
	ds_read_b128 v[148:151], v254 offset:2048
	ds_read_b128 v[198:201], v255
	ds_read_b128 v[152:155], v255 offset:2048
	ds_read_b128 v[120:123], v254 offset:4096
	ds_read_b128 v[112:115], v254 offset:6144
	ds_read_b128 v[124:127], v255 offset:4096
	ds_read_b128 v[116:119], v255 offset:6144
	v_max_f32_e32 v1, v160, v161
	v_max3_f32 v1, v1, v162, v163
	v_max3_f32 v1, v1, v164, v165
	v_max3_f32 v1, v1, v166, v167
	v_max3_f32 v1, v1, v168, v169
	v_max3_f32 v1, v1, v170, v171
	v_max3_f32 v1, v1, v172, v173
	v_max3_f32 v1, v1, v174, v175
	v_max3_f32 v1, v1, v128, v129
	v_max3_f32 v1, v1, v130, v131
	v_max3_f32 v1, v1, v132, v133
	v_max3_f32 v1, v1, v134, v135
	v_max3_f32 v1, v1, v136, v137
	v_max3_f32 v1, v1, v138, v139
	v_max3_f32 v1, v1, v140, v141
	v_max3_f32 v1, v1, v142, v143
	v_cmp_lt_f32_e32 vcc, s80, v1
	s_cbranch_vccnz .LBB0_383

; #define SBAR() __builtin_amdgcn_sched_barrier(0)
; #define MFMA8Q(A, B, C) __builtin_amdgcn_mfma_scale_f32_32x32x64_f8f6f4(A, B, C, 0, 0, 0, SCL1, 0, 0x7C7C7C7C)
; __device__ __forceinline__ v8i ld32(const char* p0, const char* p1) { const u32x4 a = *(const u32x4*)p0, b = *(const u32x4*)p1; return (v8i){(int)a.x, (int)a.y, (int)a.z, (int)a.w, (int)b.x, (int)b.y, (int)b.z, (int)b.w}; }
; #define DMA(slot, t) do { \
;     __builtin_amdgcn_global_load_lds((const unsigned*)(Kg + (long)(t) * (64 * 256)), (LAS unsigned*)(L3 + K_OFF + (slot) * SHM_T + wid * 1024), 16, 0, 0); \
;     __builtin_amdgcn_global_load_lds((const unsigned*)(Vg + (long)(t) * 8192), (LAS unsigned*)(L3 + (slot) * SHM_T + wid * 1024), 16, 0, 0); } while (0)
; __device__ __forceinline__ void finishSM(f32x16& p0, f32x16& p1, v8i& pf) {
;   for (int r = 0; r < 16; ++r) p1[r] = __builtin_amdgcn_exp2f(p1[r]);
; #pragma unroll
;   for (int j = 0; j < 4; ++j) {
;     int a = __builtin_amdgcn_cvt_pk_fp8_f32(p0[4 * j], p0[4 * j + 1], 0, false); a = __builtin_amdgcn_cvt_pk_fp8_f32(p0[4 * j + 2], p0[4 * j + 3], a, true);
;     int b = __builtin_amdgcn_cvt_pk_fp8_f32(p1[4 * j], p1[4 * j + 1], 0, false); b = __builtin_amdgcn_cvt_pk_fp8_f32(p1[4 * j + 2], p1[4 * j + 3], b, true);
;     auto rr = __builtin_amdgcn_permlane32_swap((unsigned)a, (unsigned)b, false, false);
;     pf[2 * j] = (int)rr[0]; pf[2 * j + 1] = (int)rr[1]; }
; }
; __device__ __forceinline__ void qkt(f32x16& p0, f32x16& p1, const f32x16& nm, const char* Ks, const v8i* qr, int ko, int c00, int c01, int c10, int c11) {
;   { const v8i a0 = ld32(Ks + ko + c00, Ks + ko + c01), a1 = ld32(Ks + 4096 + ko + c00, Ks + 4096 + ko + c01);
;     p0 = MFMA8Q(a0, qr[0], nm); p1 = MFMA8Q(a1, qr[0], nm); }
;   { const v8i a0 = ld32(Ks + ko + c10, Ks + ko + c11), a1 = ld32(Ks + 4096 + ko + c10, Ks + 4096 + ko + c11);
;     p0 = MFMA8Q(a0, qr[1], p0); p1 = MFMA8Q(a1, qr[1], p1); }
; }
; __device__ __forceinline__ void body(const unsigned char* Q8b, const unsigned char* K8h, const unsigned char* VT8h, const bf16_t* Gb, bf16_t* Ob, int seq, char* lds, const int wid, ...
;     ...
;     SBAR(); QKT(pA0, pA1, (s0 + 2) & 3);
;     finishSM(pB0, pB1, pf); PIPE1(); SBAR();
;     { const int t4 = (i + 4 < NT) ? i + 4 : NT - 1; DMA(s0, t4); }
;     SBAR();
;     HALF2(pA0, pA1, alA, (s0 + 1) & 3);
.Lstg_a1:
	ds_read_b128 v[2:5], v242 offset:49152
	ds_read_b128 v[6:9], v243 offset:49152
	ds_read_b128 v[112:115], v242 offset:53248
	ds_read_b128 v[116:119], v243 offset:53248
	ds_read_b128 v[194:197], v244 offset:49152
	ds_read_b128 v[198:201], v245 offset:49152
	ds_read_b128 v[246:249], v244 offset:53248
	ds_read_b128 v[250:253], v245 offset:53248
	v_exp_f32_e32 v1, v128
	v_exp_f32_e32 v10, v129
	v_exp_f32_e32 v11, v130
	v_exp_f32_e32 v12, v131
	s_waitcnt lgkmcnt(6)
	v_mfma_scale_f32_32x32x64_f8f6f4 v[160:175], v[2:9], v[176:183], v[96:111], v240, v239 op_sel_hi:[0,0,0]
	v_exp_f32_e32 v6, v132
	v_exp_f32_e32 v7, v133
	v_exp_f32_e32 v8, v134
	v_exp_f32_e32 v9, v135
	v_cvt_pk_fp8_f32 v5, v6, v7
	v_cvt_pk_fp8_f32 v2, v144, v145
	v_cvt_pk_fp8_f32 v5, v8, v9 op_sel:[0,0,1]
	s_waitcnt lgkmcnt(4)
	v_mfma_scale_f32_32x32x64_f8f6f4 v[112:127], v[112:119], v[176:183], v[96:111], v240, v239 op_sel_hi:[0,0,0]
	v_exp_f32_e32 v13, v136
	v_exp_f32_e32 v14, v137
	v_exp_f32_e32 v15, v138
	v_exp_f32_e32 v128, v139
	v_cvt_pk_fp8_f32 v3, v1, v10
	v_cvt_pk_fp8_f32 v4, v148, v149
	v_cvt_pk_fp8_f32 v6, v152, v153
	v_cvt_pk_fp8_f32 v7, v13, v14
	v_cvt_pk_fp8_f32 v8, v156, v157
	v_cvt_pk_fp8_f32 v2, v146, v147 op_sel:[0,0,1]
	v_cvt_pk_fp8_f32 v3, v11, v12 op_sel:[0,0,1]
	v_cvt_pk_fp8_f32 v4, v150, v151 op_sel:[0,0,1]
	v_cvt_pk_fp8_f32 v6, v154, v155 op_sel:[0,0,1]
	v_cvt_pk_fp8_f32 v7, v15, v128 op_sel:[0,0,1]
	v_cvt_pk_fp8_f32 v8, v158, v159 op_sel:[0,0,1]
	s_waitcnt lgkmcnt(2)
	v_mfma_scale_f32_32x32x64_f8f6f4 v[160:175], v[194:201], v[184:191], v[160:175], v240, v239 op_sel_hi:[0,0,0]
	v_exp_f32_e32 v129, v140
	v_exp_f32_e32 v130, v141
	v_exp_f32_e32 v131, v142
	v_exp_f32_e32 v132, v143
	v_cvt_pk_fp8_f32 v9, v129, v130
	s_nop 0
	v_cvt_pk_fp8_f32 v9, v131, v132 op_sel:[0,0,1]
	s_waitcnt lgkmcnt(0)
	v_mfma_scale_f32_32x32x64_f8f6f4 v[112:127], v[246:253], v[184:191], v[112:127], v240, v239 op_sel_hi:[0,0,0]
	s_min_u32 s36, s45, 0x7b
	s_add_i32 s56, s36, 4
	s_lshl_b32 s36, s56, 14
	s_add_i32 s57, s68, 0x0
	s_add_u32 s88, s94, s36
	s_addc_u32 s89, s95, 0
	s_add_i32 m0, s57, 0x8000
	s_lshl_b32 s36, s56, 13
	s_add_u32 s90, s96, s36
	s_addc_u32 s91, s97, 0
	global_load_lds_dwordx4 v192, s[88:89]
	s_mov_b32 m0, s57
	s_nop 0
	global_load_lds_dwordx4 v193, s[90:91]
	ds_read_b128 v[194:197], v254 offset:8192
	ds_read_b128 v[148:151], v254 offset:10240
	ds_read_b128 v[198:201], v255 offset:8192
	ds_read_b128 v[152:155], v255 offset:10240
	ds_read_b128 v[136:139], v254 offset:12288
	ds_read_b128 v[128:131], v254 offset:14336
	ds_read_b128 v[140:143], v255 offset:12288
	ds_read_b128 v[132:135], v255 offset:14336
	v_max_f32_e32 v1, v160, v161
	v_max3_f32 v1, v1, v162, v163
	v_max3_f32 v1, v1, v164, v165
	v_max3_f32 v1, v1, v166, v167
	v_max3_f32 v1, v1, v168, v169
	v_max3_f32 v1, v1, v170, v171
	v_max3_f32 v1, v1, v172, v173
	v_max3_f32 v1, v1, v174, v175
	v_max3_f32 v1, v1, v112, v113
	v_max3_f32 v1, v1, v114, v115
	v_max3_f32 v1, v1, v116, v117
	v_max3_f32 v1, v1, v118, v119
	v_max3_f32 v1, v1, v120, v121
	v_max3_f32 v1, v1, v122, v123
	v_max3_f32 v1, v1, v124, v125
	v_max3_f32 v1, v1, v126, v127
	v_cmp_lt_f32_e32 vcc, s80, v1
	s_cbranch_vccnz .LBB0_384

; #define SBAR() __builtin_amdgcn_sched_barrier(0)
; #define MFMA8Q(A, B, C) __builtin_amdgcn_mfma_scale_f32_32x32x64_f8f6f4(A, B, C, 0, 0, 0, SCL1, 0, 0x7C7C7C7C)
; __device__ __forceinline__ v8i ld32(const char* p0, const char* p1) { const u32x4 a = *(const u32x4*)p0, b = *(const u32x4*)p1; return (v8i){(int)a.x, (int)a.y, (int)a.z, (int)a.w, (int)b.x, (int)b.y, (int)b.z, (int)b.w}; }
; #define DMA(slot, t) do { \
;     __builtin_amdgcn_global_load_lds((const unsigned*)(Kg + (long)(t) * (64 * 256)), (LAS unsigned*)(L3 + K_OFF + (slot) * SHM_T + wid * 1024), 16, 0, 0); \
;     __builtin_amdgcn_global_load_lds((const unsigned*)(Vg + (long)(t) * 8192), (LAS unsigned*)(L3 + (slot) * SHM_T + wid * 1024), 16, 0, 0); } while (0)
; #define QKT(P0, P1, b) qkt(P0, P1, nm, K_lds + (b) * SHM_T, qr, ko, c00, c01, c10, c11)
; __device__ __forceinline__ void finishSM(f32x16& p0, f32x16& p1, v8i& pf) {
;   for (int r = 0; r < 16; ++r) p1[r] = __builtin_amdgcn_exp2f(p1[r]);
; #pragma unroll
;   for (int j = 0; j < 4; ++j) {
;     int a = __builtin_amdgcn_cvt_pk_fp8_f32(p0[4 * j], p0[4 * j + 1], 0, false); a = __builtin_amdgcn_cvt_pk_fp8_f32(p0[4 * j + 2], p0[4 * j + 3], a, true);
;     int b = __builtin_amdgcn_cvt_pk_fp8_f32(p1[4 * j], p1[4 * j + 1], 0, false); b = __builtin_amdgcn_cvt_pk_fp8_f32(p1[4 * j + 2], p1[4 * j + 3], b, true);
;     auto rr = __builtin_amdgcn_permlane32_swap((unsigned)a, (unsigned)b, false, false);
;     pf[2 * j] = (int)rr[0]; pf[2 * j + 1] = (int)rr[1]; }
; }
; __device__ __forceinline__ void qkt(f32x16& p0, f32x16& p1, const f32x16& nm, const char* Ks, const v8i* qr, int ko, int c00, int c01, int c10, int c11) {
;   { const v8i a0 = ld32(Ks + ko + c00, Ks + ko + c01), a1 = ld32(Ks + 4096 + ko + c00, Ks + 4096 + ko + c01);
;     p0 = MFMA8Q(a0, qr[0], nm); p1 = MFMA8Q(a1, qr[0], nm); }
;   { const v8i a0 = ld32(Ks + ko + c10, Ks + ko + c11), a1 = ld32(Ks + 4096 + ko + c10, Ks + 4096 + ko + c11);
;     p0 = MFMA8Q(a0, qr[1], p0); p1 = MFMA8Q(a1, qr[1], p1); }
; }
; __device__ __forceinline__ void body(const unsigned char* Q8b, const unsigned char* K8h, const unsigned char* VT8h, const bf16_t* Gb, bf16_t* Ob, int seq, char* lds, const int wid, ...
;     ...
;     SBAR(); QKT(pB0, pB1, (s0 + 1) & 3);
;     finishSM(pA0, pA1, pf); PIPE1(); SBAR();
;     DMA((s0 + 3) & 3, i + 3);
;     SBAR();
;     HALF2(pB0, pB1, alB, s0);
.Lc2_374:
	ds_read_b128 v[2:5], v242 offset:57344
	ds_read_b128 v[6:9], v243 offset:57344
	ds_read_b128 v[128:131], v242 offset:61440
	ds_read_b128 v[132:135], v243 offset:61440
	ds_read_b128 v[194:197], v244 offset:57344
	ds_read_b128 v[198:201], v245 offset:57344
	ds_read_b128 v[246:249], v244 offset:61440
	ds_read_b128 v[250:253], v245 offset:61440
	v_exp_f32_e32 v1, v112
	v_exp_f32_e32 v10, v113
	v_exp_f32_e32 v11, v114
	v_exp_f32_e32 v12, v115
	s_waitcnt lgkmcnt(6)
	v_mfma_scale_f32_32x32x64_f8f6f4 v[160:175], v[2:9], v[176:183], v[96:111], v240, v239 op_sel_hi:[0,0,0]
	v_exp_f32_e32 v6, v116
	v_exp_f32_e32 v7, v117
	v_exp_f32_e32 v8, v118
	v_exp_f32_e32 v9, v119
	v_cvt_pk_fp8_f32 v5, v6, v7
	v_cvt_pk_fp8_f32 v3, v1, v10
	v_cvt_pk_fp8_f32 v5, v8, v9 op_sel:[0,0,1]
	s_waitcnt lgkmcnt(4)
	v_mfma_scale_f32_32x32x64_f8f6f4 v[128:143], v[128:135], v[176:183], v[96:111], v240, v239 op_sel_hi:[0,0,0]
	v_exp_f32_e32 v13, v120
	v_exp_f32_e32 v14, v121
	v_exp_f32_e32 v15, v122
	v_exp_f32_e32 v112, v123
	v_cvt_pk_fp8_f32 v2, v144, v145
	v_cvt_pk_fp8_f32 v4, v148, v149
	v_cvt_pk_fp8_f32 v6, v152, v153
	v_cvt_pk_fp8_f32 v7, v13, v14
	v_cvt_pk_fp8_f32 v8, v156, v157
	v_cvt_pk_fp8_f32 v2, v146, v147 op_sel:[0,0,1]
	v_cvt_pk_fp8_f32 v3, v11, v12 op_sel:[0,0,1]
	v_cvt_pk_fp8_f32 v4, v150, v151 op_sel:[0,0,1]
	v_cvt_pk_fp8_f32 v6, v154, v155 op_sel:[0,0,1]
	v_cvt_pk_fp8_f32 v7, v15, v112 op_sel:[0,0,1]
	v_cvt_pk_fp8_f32 v8, v158, v159 op_sel:[0,0,1]
	s_waitcnt lgkmcnt(2)
	v_mfma_scale_f32_32x32x64_f8f6f4 v[160:175], v[194:201], v[184:191], v[160:175], v240, v239 op_sel_hi:[0,0,0]
	v_exp_f32_e32 v113, v124
	v_exp_f32_e32 v114, v125
	v_exp_f32_e32 v1, v126
	v_exp_f32_e32 v10, v127
	v_cvt_pk_fp8_f32 v9, v113, v114
	s_nop 0
	v_cvt_pk_fp8_f32 v9, v1, v10 op_sel:[0,0,1]
	s_waitcnt lgkmcnt(0)
	v_mfma_scale_f32_32x32x64_f8f6f4 v[128:143], v[246:253], v[184:191], v[128:143], v240, v239 op_sel_hi:[0,0,0]
	s_add_i32 m0, s68, 0xa000
	s_nop 0
	global_load_lds_dwordx4 v192, s[98:99]
	s_add_i32 m0, s68, 0x2000
	s_nop 0
	global_load_lds_dwordx4 v193, s[100:101]
	ds_read_b128 v[194:197], v254 offset:16384
	ds_read_b128 v[148:151], v254 offset:18432
	ds_read_b128 v[198:201], v255 offset:16384
	ds_read_b128 v[152:155], v255 offset:18432
	ds_read_b128 v[120:123], v254 offset:20480
	ds_read_b128 v[112:115], v254 offset:22528
	ds_read_b128 v[124:127], v255 offset:20480
	ds_read_b128 v[116:119], v255 offset:22528
	v_max_f32_e32 v1, v160, v161
	v_max3_f32 v1, v1, v162, v163
	v_max3_f32 v1, v1, v164, v165
	v_max3_f32 v1, v1, v166, v167
	v_max3_f32 v1, v1, v168, v169
	v_max3_f32 v1, v1, v170, v171
	v_max3_f32 v1, v1, v172, v173
	v_max3_f32 v1, v1, v174, v175
	v_max3_f32 v1, v1, v128, v129
	v_max3_f32 v1, v1, v130, v131
	v_max3_f32 v1, v1, v132, v133
	v_max3_f32 v1, v1, v134, v135
	v_max3_f32 v1, v1, v136, v137
	v_max3_f32 v1, v1, v138, v139
	v_max3_f32 v1, v1, v140, v141
	v_max3_f32 v1, v1, v142, v143
	v_cmp_lt_f32_e32 vcc, s80, v1
	s_cbranch_vccnz .Lc2_383

; #define SBAR() __builtin_amdgcn_sched_barrier(0)
; #define MFMA8Q(A, B, C) __builtin_amdgcn_mfma_scale_f32_32x32x64_f8f6f4(A, B, C, 0, 0, 0, SCL1, 0, 0x7C7C7C7C)
; __device__ __forceinline__ v8i ld32(const char* p0, const char* p1) { const u32x4 a = *(const u32x4*)p0, b = *(const u32x4*)p1; return (v8i){(int)a.x, (int)a.y, (int)a.z, (int)a.w, (int)b.x, (int)b.y, (int)b.z, (int)b.w}; }
; #define DMA(slot, t) do { \
;     __builtin_amdgcn_global_load_lds((const unsigned*)(Kg + (long)(t) * (64 * 256)), (LAS unsigned*)(L3 + K_OFF + (slot) * SHM_T + wid * 1024), 16, 0, 0); \
;     __builtin_amdgcn_global_load_lds((const unsigned*)(Vg + (long)(t) * 8192), (LAS unsigned*)(L3 + (slot) * SHM_T + wid * 1024), 16, 0, 0); } while (0)
; __device__ __forceinline__ void finishSM(f32x16& p0, f32x16& p1, v8i& pf) {
;   for (int r = 0; r < 16; ++r) p1[r] = __builtin_amdgcn_exp2f(p1[r]);
; #pragma unroll
;   for (int j = 0; j < 4; ++j) {
;     int a = __builtin_amdgcn_cvt_pk_fp8_f32(p0[4 * j], p0[4 * j + 1], 0, false); a = __builtin_amdgcn_cvt_pk_fp8_f32(p0[4 * j + 2], p0[4 * j + 3], a, true);
;     int b = __builtin_amdgcn_cvt_pk_fp8_f32(p1[4 * j], p1[4 * j + 1], 0, false); b = __builtin_amdgcn_cvt_pk_fp8_f32(p1[4 * j + 2], p1[4 * j + 3], b, true);
;     auto rr = __builtin_amdgcn_permlane32_swap((unsigned)a, (unsigned)b, false, false);
;     pf[2 * j] = (int)rr[0]; pf[2 * j + 1] = (int)rr[1]; }
; }
; __device__ __forceinline__ void qkt(f32x16& p0, f32x16& p1, const f32x16& nm, const char* Ks, const v8i* qr, int ko, int c00, int c01, int c10, int c11) {
;   { const v8i a0 = ld32(Ks + ko + c00, Ks + ko + c01), a1 = ld32(Ks + 4096 + ko + c00, Ks + 4096 + ko + c01);
;     p0 = MFMA8Q(a0, qr[0], nm); p1 = MFMA8Q(a1, qr[0], nm); }
;   { const v8i a0 = ld32(Ks + ko + c10, Ks + ko + c11), a1 = ld32(Ks + 4096 + ko + c10, Ks + 4096 + ko + c11);
;     p0 = MFMA8Q(a0, qr[1], p0); p1 = MFMA8Q(a1, qr[1], p1); }
; }
; __device__ __forceinline__ void body(const unsigned char* Q8b, const unsigned char* K8h, const unsigned char* VT8h, const bf16_t* Gb, bf16_t* Ob, int seq, char* lds, const int wid, ...
;     ...
;     SBAR(); QKT(pA0, pA1, (s0 + 2) & 3);
;     finishSM(pB0, pB1, pf); PIPE1(); SBAR();
;     { const int t4 = (i + 4 < NT) ? i + 4 : NT - 1; DMA(s0, t4); }
;     SBAR();
;     HALF2(pA0, pA1, alA, (s0 + 1) & 3);
.Lc2stg_a1:
	ds_read_b128 v[2:5], v242 offset:32768
	ds_read_b128 v[6:9], v243 offset:32768
	ds_read_b128 v[112:115], v242 offset:36864
	ds_read_b128 v[116:119], v243 offset:36864
	ds_read_b128 v[194:197], v244 offset:32768
	ds_read_b128 v[198:201], v245 offset:32768
	ds_read_b128 v[246:249], v244 offset:36864
	ds_read_b128 v[250:253], v245 offset:36864
	v_exp_f32_e32 v1, v128
	v_exp_f32_e32 v10, v129
	v_exp_f32_e32 v11, v130
	v_exp_f32_e32 v12, v131
	s_waitcnt lgkmcnt(6)
	v_mfma_scale_f32_32x32x64_f8f6f4 v[160:175], v[2:9], v[176:183], v[96:111], v240, v239 op_sel_hi:[0,0,0]
	v_exp_f32_e32 v6, v132
	v_exp_f32_e32 v7, v133
	v_exp_f32_e32 v8, v134
	v_exp_f32_e32 v9, v135
	v_cvt_pk_fp8_f32 v5, v6, v7
	v_cvt_pk_fp8_f32 v2, v144, v145
	v_cvt_pk_fp8_f32 v5, v8, v9 op_sel:[0,0,1]
	s_waitcnt lgkmcnt(4)
	v_mfma_scale_f32_32x32x64_f8f6f4 v[112:127], v[112:119], v[176:183], v[96:111], v240, v239 op_sel_hi:[0,0,0]
	v_exp_f32_e32 v13, v136
	v_exp_f32_e32 v14, v137
	v_exp_f32_e32 v15, v138
	v_exp_f32_e32 v128, v139
	v_cvt_pk_fp8_f32 v3, v1, v10
	v_cvt_pk_fp8_f32 v4, v148, v149
	v_cvt_pk_fp8_f32 v6, v152, v153
	v_cvt_pk_fp8_f32 v7, v13, v14
	v_cvt_pk_fp8_f32 v8, v156, v157
	v_cvt_pk_fp8_f32 v2, v146, v147 op_sel:[0,0,1]
	v_cvt_pk_fp8_f32 v3, v11, v12 op_sel:[0,0,1]
	v_cvt_pk_fp8_f32 v4, v150, v151 op_sel:[0,0,1]
	v_cvt_pk_fp8_f32 v6, v154, v155 op_sel:[0,0,1]
	v_cvt_pk_fp8_f32 v7, v15, v128 op_sel:[0,0,1]
	v_cvt_pk_fp8_f32 v8, v158, v159 op_sel:[0,0,1]
	s_waitcnt lgkmcnt(2)
	v_mfma_scale_f32_32x32x64_f8f6f4 v[160:175], v[194:201], v[184:191], v[160:175], v240, v239 op_sel_hi:[0,0,0]
	v_exp_f32_e32 v129, v140
	v_exp_f32_e32 v130, v141
	v_exp_f32_e32 v131, v142
	v_exp_f32_e32 v132, v143
	v_cvt_pk_fp8_f32 v9, v129, v130
	s_nop 0
	v_cvt_pk_fp8_f32 v9, v131, v132 op_sel:[0,0,1]
	s_waitcnt lgkmcnt(0)
	v_mfma_scale_f32_32x32x64_f8f6f4 v[112:127], v[246:253], v[184:191], v[112:127], v240, v239 op_sel_hi:[0,0,0]
	s_min_u32 s36, s45, 0x7b
	s_add_i32 s56, s36, 4
	s_lshl_b32 s36, s56, 14
	s_add_i32 s57, s68, 0x4000
	s_add_u32 s88, s94, s36
	s_addc_u32 s89, s95, 0
	s_add_i32 m0, s57, 0x8000
	s_lshl_b32 s36, s56, 13
	s_add_u32 s90, s96, s36
	s_addc_u32 s91, s97, 0
	global_load_lds_dwordx4 v192, s[88:89]
	s_mov_b32 m0, s57
	s_nop 0
	global_load_lds_dwordx4 v193, s[90:91]
	ds_read_b128 v[194:197], v254 offset:24576
	ds_read_b128 v[148:151], v254 offset:26624
	ds_read_b128 v[198:201], v255 offset:24576
	ds_read_b128 v[152:155], v255 offset:26624
	ds_read_b128 v[136:139], v254 offset:28672
	ds_read_b128 v[128:131], v254 offset:30720
	ds_read_b128 v[140:143], v255 offset:28672
	ds_read_b128 v[132:135], v255 offset:30720
	v_max_f32_e32 v1, v160, v161
	v_max3_f32 v1, v1, v162, v163
	v_max3_f32 v1, v1, v164, v165
	v_max3_f32 v1, v1, v166, v167
	v_max3_f32 v1, v1, v168, v169
	v_max3_f32 v1, v1, v170, v171
	v_max3_f32 v1, v1, v172, v173
	v_max3_f32 v1, v1, v174, v175
	v_max3_f32 v1, v1, v112, v113
	v_max3_f32 v1, v1, v114, v115
	v_max3_f32 v1, v1, v116, v117
	v_max3_f32 v1, v1, v118, v119
	v_max3_f32 v1, v1, v120, v121
	v_max3_f32 v1, v1, v122, v123
	v_max3_f32 v1, v1, v124, v125
	v_max3_f32 v1, v1, v126, v127
	v_cmp_lt_f32_e32 vcc, s80, v1
	s_cbranch_vccnz .Lc2_384
